# scan producer: gate loads and OG stores as 16-byte accesses (8 consecutive dv per thread, full 128B lines per token row) + V-chunk staging coalesced; row-norm via FMA chains and DPP reduce
# speedup vs baseline: 1.2479x; 1.0056x over previous
.LBB0_280:
	s_or_b64 exec, exec, s[0:1]
	v_readlane_b32 s8, v251, 39
	v_readlane_b32 s9, v251, 40
	s_ashr_i32 s14, s15, 6
	v_and_b32_e32 v174, 63, v161
	v_cndmask_b32_e64 v1, 0, 1, s[8:9]
	v_and_b32_e32 v0, 15, v161
	v_bfe_u32 v47, v161, 4, 2
	s_mov_b64 s[0:1], -1
	s_cmp_lt_i32 s14, 4
	v_cmp_ne_u32_e64 s[38:39], 1, v1
	s_cbranch_scc1 .LBB0_312
	s_and_b64 vcc, exec, s[38:39]
	s_cbranch_vccnz .LBB0_311
	v_add_u32_e32 v53, 0xffffff00, v161
	v_ashrrev_i32_e32 v175, 3, v53
	s_movk_i32 s0, 0x410
	v_lshl_or_b32 v1, s14, 4, v0
	s_waitcnt lgkmcnt(0)
	v_mul_lo_u32 v3, v175, s0
	v_readlane_b32 s0, v254, 38
	s_waitcnt vmcnt(0)
	v_subrev_u32_e32 v6, 64, v1
	v_and_b32_e32 v1, 7, v161
	v_add_u32_e32 v7, s0, v3
	v_readlane_b32 s0, v253, 53
	v_lshlrev_b32_e32 v4, 4, v1
	v_mov_b32_e32 v5, v2
	v_readlane_b32 s1, v253, 54
	v_lshlrev_b32_e32 v176, 3, v47
	v_lshlrev_b32_e32 v9, 1, v161
	v_lshl_add_u64 v[36:37], s[0:1], 0, v[4:5]
	v_readlane_b32 s0, v251, 22
	v_readlane_b32 s1, v251, 23
	v_lshlrev_b32_e32 v8, 5, v1
	v_lshl_add_u32 v177, v53, 6, 0
	v_lshl_add_u64 v[38:39], s[0:1], 0, v[4:5]
	s_movk_i32 s0, 0xa0
	v_mul_lo_u32 v5, v6, s0
	s_movk_i32 s0, 0xff68
	v_add_u32_e32 v185, 0, v5
	v_mul_lo_u32 v186, v6, s0
	v_lshlrev_b32_e32 v4, 2, v6
	v_add_u32_e32 v187, v185, v186
	v_sub_u32_e32 v46, v187, v4
	s_movk_i32 s0, 0x9c
	v_or_b32_e32 v40, 2, v176
	v_or_b32_e32 v3, 3, v176
	v_or_b32_e32 v43, 4, v176
	v_or_b32_e32 v42, 5, v176
	v_or_b32_e32 v45, 6, v176
	v_or_b32_e32 v44, 7, v176
	s_mov_b32 s98, 0x110000
	s_mov_b32 s99, 0
	v_lshlrev_b32_e32 v182, 4, v53
	v_and_b32_e32 v182, 0xffffffc0, v182
	v_bfe_u32 v183, v53, 4, 2
	v_and_b32_e32 v180, 3, v53
	v_lshlrev_b32_e32 v180, 1, v180
	v_xor_b32_e32 v180, v180, v183
	v_lshlrev_b32_e32 v180, 3, v180
	v_add_u32_e32 v180, v180, v182
	v_add_u32_e32 v180, 0xd800, v180
	v_xor_b32_e32 v181, 8, v180
	v_add_u32_e32 v9, 0, v4
	v_mul_u32_u24_e32 v184, 0x840, v47
	v_mad_u64_u32 v[48:49], s[0:1], v6, s0, v[46:47]
	v_lshlrev_b32_e32 v55, 1, v6
	v_add_u32_e32 v178, 0xd800, v177
	v_cmp_gt_u32_e64 s[40:41], 16, v174
	v_cmp_lt_u32_e64 s[42:43], 31, v174
	v_and_b32_e32 v179, 48, v161
	v_or_b32_e32 v1, 1, v176
	v_pk_mov_b32 v[50:51], v[44:45], v[42:43] op_sel:[1,0]
	v_mov_b32_e32 v52, v43
	v_mov_b32_e32 v54, v3
	v_mov_b32_e32 v41, v40
	v_add_u32_e32 v49, v9, v184
	v_add_u32_e32 v188, v7, v8
	s_mov_b32 s16, s2
	s_branch .LBB0_284

.LBB0_295:
	ds_read_b128 v[130:133], v188
	ds_read_b128 v[134:137], v188 offset:16
	ds_read_b128 v[138:141], v188 offset:256
	ds_read_b128 v[142:145], v188 offset:272
	ds_read_b128 v[146:149], v188 offset:512
	ds_read_b128 v[150:153], v188 offset:528
	ds_read_b128 v[154:157], v188 offset:768
	ds_read_b128 v[166:169], v188 offset:784
	s_sub_i32 s0, s8, s25
	v_cmp_gt_i32_e32 vcc, s26, v175
	s_min_i32 s1, s24, s20
	s_lshl_b32 s1, s1, 5
	s_sub_i32 s25, s17, s1
	v_lshlrev_b32_e32 v172, 16, v126
	v_and_b32_e32 v173, 0xffff0000, v126
	s_cmp_gt_i32 s25, 31
	s_waitcnt lgkmcnt(6)
	v_mul_f32_e32 v238, v130, v130
	v_mul_f32_e32 v239, v131, v131
	v_mul_f32_e32 v240, v132, v132
	v_mul_f32_e32 v241, v133, v133
	v_fmac_f32_e32 v238, v134, v134
	v_fmac_f32_e32 v239, v135, v135
	v_fmac_f32_e32 v240, v136, v136
	v_fmac_f32_e32 v241, v137, v137
	s_waitcnt lgkmcnt(4)
	v_fmac_f32_e32 v238, v138, v138
	v_fmac_f32_e32 v239, v139, v139
	v_fmac_f32_e32 v240, v140, v140
	v_fmac_f32_e32 v241, v141, v141
	v_fmac_f32_e32 v238, v142, v142
	v_fmac_f32_e32 v239, v143, v143
	v_fmac_f32_e32 v240, v144, v144
	v_fmac_f32_e32 v241, v145, v145
	s_waitcnt lgkmcnt(2)
	v_fmac_f32_e32 v238, v146, v146
	v_fmac_f32_e32 v239, v147, v147
	v_fmac_f32_e32 v240, v148, v148
	v_fmac_f32_e32 v241, v149, v149
	v_fmac_f32_e32 v238, v150, v150
	v_fmac_f32_e32 v239, v151, v151
	v_fmac_f32_e32 v240, v152, v152
	v_fmac_f32_e32 v241, v153, v153
	s_waitcnt lgkmcnt(0)
	v_fmac_f32_e32 v238, v154, v154
	v_fmac_f32_e32 v239, v155, v155
	v_fmac_f32_e32 v240, v156, v156
	v_fmac_f32_e32 v241, v157, v157
	v_fmac_f32_e32 v238, v166, v166
	v_fmac_f32_e32 v239, v167, v167
	v_fmac_f32_e32 v240, v168, v168
	v_fmac_f32_e32 v241, v169, v169
	v_add_f32_e32 v238, v238, v239
	v_add_f32_e32 v240, v240, v241
	v_add_f32_e32 v158, v238, v240
	s_nop 1
	v_add_f32_dpp v158, v158, v158 quad_perm:[1,0,3,2] row_mask:0xf bank_mask:0xf
	s_nop 1
	v_add_f32_dpp v158, v158, v158 quad_perm:[2,3,0,1] row_mask:0xf bank_mask:0xf
	s_nop 1
	v_add_f32_dpp v158, v158, v158 row_half_mirror row_mask:0xf bank_mask:0xf
	v_fmamk_f32 v158, v158, 0x3b800000, v206
	v_rsq_f32_e32 v158, v158
	v_mov_b32_e32 v159, s0
	v_cndmask_b32_e32 v159, v210, v159, vcc
	v_add_u32_e32 v170, v159, v175
	v_ashrrev_i32_e32 v171, 31, v170
	v_lshlrev_b64 v[170:171], 13, v[170:171]
	v_lshl_add_u64 v[170:171], v[74:75], 0, v[170:171]
	v_pk_mul_f32 v[130:131], v[130:131], v[158:159] op_sel_hi:[1,0]
	v_lshlrev_b32_e32 v238, 16, v80
	v_and_b32_e32 v239, 0xffff0000, v80
	v_pk_mul_f32 v[130:131], v[130:131], v[238:239]
	v_cvt_pk_bf16_f32 v80, v130, v131
	v_pk_mul_f32 v[132:133], v[132:133], v[158:159] op_sel_hi:[1,0]
	v_lshlrev_b32_e32 v238, 16, v81
	v_and_b32_e32 v239, 0xffff0000, v81
	v_pk_mul_f32 v[132:133], v[132:133], v[238:239]
	v_cvt_pk_bf16_f32 v81, v132, v133
	v_pk_mul_f32 v[134:135], v[134:135], v[158:159] op_sel_hi:[1,0]
	v_lshlrev_b32_e32 v238, 16, v82
	v_and_b32_e32 v239, 0xffff0000, v82
	v_pk_mul_f32 v[134:135], v[134:135], v[238:239]
	v_cvt_pk_bf16_f32 v82, v134, v135
	v_pk_mul_f32 v[136:137], v[136:137], v[158:159] op_sel_hi:[1,0]
	v_lshlrev_b32_e32 v238, 16, v83
	v_and_b32_e32 v239, 0xffff0000, v83
	v_pk_mul_f32 v[136:137], v[136:137], v[238:239]
	v_cvt_pk_bf16_f32 v83, v136, v137
	global_store_dwordx4 v[170:171], v[80:83], off
	v_pk_mul_f32 v[138:139], v[138:139], v[158:159] op_sel_hi:[1,0]
	v_lshlrev_b32_e32 v238, 16, v84
	v_and_b32_e32 v239, 0xffff0000, v84
	v_pk_mul_f32 v[138:139], v[138:139], v[238:239]
	v_cvt_pk_bf16_f32 v84, v138, v139
	v_pk_mul_f32 v[140:141], v[140:141], v[158:159] op_sel_hi:[1,0]
	v_lshlrev_b32_e32 v238, 16, v85
	v_and_b32_e32 v239, 0xffff0000, v85
	v_pk_mul_f32 v[140:141], v[140:141], v[238:239]
	v_cvt_pk_bf16_f32 v85, v140, v141
	v_pk_mul_f32 v[142:143], v[142:143], v[158:159] op_sel_hi:[1,0]
	v_lshlrev_b32_e32 v238, 16, v86
	v_and_b32_e32 v239, 0xffff0000, v86
	v_pk_mul_f32 v[142:143], v[142:143], v[238:239]
	v_cvt_pk_bf16_f32 v86, v142, v143
	v_pk_mul_f32 v[144:145], v[144:145], v[158:159] op_sel_hi:[1,0]
	v_lshlrev_b32_e32 v238, 16, v87
	v_and_b32_e32 v239, 0xffff0000, v87
	v_pk_mul_f32 v[144:145], v[144:145], v[238:239]
	v_cvt_pk_bf16_f32 v87, v144, v145
	global_store_dwordx4 v[170:171], v[84:87], off offset:128
	v_pk_mul_f32 v[146:147], v[146:147], v[158:159] op_sel_hi:[1,0]
	v_lshlrev_b32_e32 v238, 16, v92
	v_and_b32_e32 v239, 0xffff0000, v92
	v_pk_mul_f32 v[146:147], v[146:147], v[238:239]
	v_cvt_pk_bf16_f32 v92, v146, v147
	v_pk_mul_f32 v[148:149], v[148:149], v[158:159] op_sel_hi:[1,0]
	v_lshlrev_b32_e32 v238, 16, v93
	v_and_b32_e32 v239, 0xffff0000, v93
	v_pk_mul_f32 v[148:149], v[148:149], v[238:239]
	v_cvt_pk_bf16_f32 v93, v148, v149
	v_pk_mul_f32 v[150:151], v[150:151], v[158:159] op_sel_hi:[1,0]
	v_lshlrev_b32_e32 v238, 16, v94
	v_and_b32_e32 v239, 0xffff0000, v94
	v_pk_mul_f32 v[150:151], v[150:151], v[238:239]
	v_cvt_pk_bf16_f32 v94, v150, v151
	v_pk_mul_f32 v[152:153], v[152:153], v[158:159] op_sel_hi:[1,0]
	v_lshlrev_b32_e32 v238, 16, v95
	v_and_b32_e32 v239, 0xffff0000, v95
	v_pk_mul_f32 v[152:153], v[152:153], v[238:239]
	v_cvt_pk_bf16_f32 v95, v152, v153
	global_store_dwordx4 v[170:171], v[92:95], off offset:256
	v_pk_mul_f32 v[154:155], v[154:155], v[158:159] op_sel_hi:[1,0]
	v_lshlrev_b32_e32 v238, 16, v96
	v_and_b32_e32 v239, 0xffff0000, v96
	v_pk_mul_f32 v[154:155], v[154:155], v[238:239]
	v_cvt_pk_bf16_f32 v96, v154, v155
	v_pk_mul_f32 v[156:157], v[156:157], v[158:159] op_sel_hi:[1,0]
	v_lshlrev_b32_e32 v238, 16, v97
	v_and_b32_e32 v239, 0xffff0000, v97
	v_pk_mul_f32 v[156:157], v[156:157], v[238:239]
	v_cvt_pk_bf16_f32 v97, v156, v157
	v_pk_mul_f32 v[166:167], v[166:167], v[158:159] op_sel_hi:[1,0]
	v_lshlrev_b32_e32 v238, 16, v98
	v_and_b32_e32 v239, 0xffff0000, v98
	v_pk_mul_f32 v[166:167], v[166:167], v[238:239]
	v_cvt_pk_bf16_f32 v98, v166, v167
	v_pk_mul_f32 v[168:169], v[168:169], v[158:159] op_sel_hi:[1,0]
	v_lshlrev_b32_e32 v238, 16, v99
	v_and_b32_e32 v239, 0xffff0000, v99
	v_pk_mul_f32 v[168:169], v[168:169], v[238:239]
	v_cvt_pk_bf16_f32 v99, v168, v169
	global_store_dwordx4 v[170:171], v[96:99], off offset:384
	s_waitcnt vmcnt(4)
	v_lshlrev_b32_e32 v168, 16, v232
	v_add_u32_e32 v238, s1, v217
	v_ashrrev_i32_e32 v239, 31, v238
	v_lshlrev_b64 v[238:239], 13, v[238:239]
	v_lshl_add_u64 v[238:239], v[78:79], 0, v[238:239]
	global_load_dwordx4 v[80:83], v[238:239], off
	global_load_dwordx4 v[84:87], v[238:239], off offset:128
	global_load_dwordx4 v[92:95], v[238:239], off offset:256
	global_load_dwordx4 v[96:99], v[238:239], off offset:384
	s_mov_b64 s[0:1], -1
	v_lshlrev_b32_e32 v170, 16, v234
	v_lshlrev_b32_e32 v166, 16, v231
	v_lshlrev_b32_e32 v158, 16, v229
	s_cbranch_scc1 .LBB0_297
	s_min_i32 s0, s25, 32
	v_add_f32_e32 v130, 0, v106
	v_cmp_gt_i32_e32 vcc, s0, v176
	v_and_b32_e32 v132, 0xffff0000, v235
	v_and_b32_e32 v134, 0xffff0000, v234
	v_cndmask_b32_e32 v136, 0, v130, vcc
	v_add_f32_e32 v130, 0, v107
	v_cndmask_b32_e32 v139, 0, v130, vcc
	v_lshlrev_b32_e32 v130, 16, v233
	v_cndmask_b32_e32 v131, 0, v130, vcc
	v_and_b32_e32 v130, 0xffff0000, v233
	v_cndmask_b32_e32 v241, 0, v130, vcc
	v_cmp_gt_i32_e32 vcc, s0, v1
	v_lshlrev_b32_e32 v130, 16, v235
	v_and_b32_e32 v135, 0xffff0000, v232
	v_cndmask_b32_e32 v133, 0, v102, vcc
	v_add_f32_e32 v138, v136, v133
	v_cndmask_b32_e32 v239, 0, v130, vcc
	v_cndmask_b32_e32 v240, 0, v132, vcc
	v_cndmask_b32_e32 v133, 0, v103, vcc
	v_cmp_gt_i32_e32 vcc, s0, v40
	v_and_b32_e32 v137, 0xffff0000, v231
	v_and_b32_e32 v140, 0xffff0000, v229
	v_cndmask_b32_e32 v132, 0, v118, vcc
	v_cmp_gt_i32_e32 vcc, s0, v41
	v_pk_add_f32 v[146:147], v[132:133], v[138:139]
	v_lshlrev_b32_e32 v159, 16, v236
	v_cndmask_b32_e32 v157, 0, v134, vcc
	v_cndmask_b32_e32 v156, 0, v170, vcc
	v_cndmask_b32_e32 v133, 0, v119, vcc
	v_cmp_gt_i32_e32 vcc, s0, v54
	v_lshlrev_b32_e32 v162, 16, v237
	v_and_b32_e32 v163, 0xffff0000, v236
	v_cndmask_b32_e32 v132, 0, v114, vcc
	v_cmp_gt_i32_e32 vcc, s0, v3
	v_pk_add_f32 v[148:149], v[132:133], v[146:147]
	s_nop 0
	v_cndmask_b32_e32 v155, 0, v135, vcc
	v_cndmask_b32_e32 v154, 0, v168, vcc
	v_cndmask_b32_e32 v133, 0, v115, vcc
	v_cmp_gt_i32_e32 vcc, s0, v52
	s_nop 1
	v_cndmask_b32_e32 v132, 0, v100, vcc
	v_cmp_gt_i32_e32 vcc, s0, v43
	v_pk_add_f32 v[142:143], v[132:133], v[148:149]
	s_nop 0
	v_cndmask_b32_e32 v153, 0, v137, vcc
	v_cndmask_b32_e32 v152, 0, v166, vcc
	v_cndmask_b32_e32 v133, 0, v101, vcc
	v_cmp_gt_i32_e32 vcc, s0, v42
	s_nop 1
	v_cndmask_b32_e32 v132, 0, v90, vcc
	v_cmp_gt_i32_e32 vcc, s0, v51
	v_pk_add_f32 v[144:145], v[132:133], v[142:143]
	s_nop 0
	v_cndmask_b32_e32 v151, 0, v140, vcc
	v_cndmask_b32_e32 v150, 0, v158, vcc
	v_cndmask_b32_e32 v133, 0, v91, vcc
	v_cmp_gt_i32_e32 vcc, s0, v50
	s_nop 1
	v_cndmask_b32_e32 v132, 0, v108, vcc
	v_cmp_gt_i32_e32 vcc, s0, v45
	v_cmp_gt_i32_e64 s[0:1], s0, v44
	v_pk_add_f32 v[140:141], v[132:133], v[144:145]
	v_cndmask_b32_e32 v133, 0, v109, vcc
	v_cndmask_b32_e64 v132, 0, v128, s[0:1]
	v_cndmask_b32_e32 v130, 0, v159, vcc
	v_pk_add_f32 v[134:135], v[132:133], v[140:141]
	v_cndmask_b32_e64 v132, 0, v129, s[0:1]
	v_and_b32_e32 v159, 0xffff0000, v237
	v_add_f32_e32 v137, v132, v135
	v_cndmask_b32_e32 v133, 0, v163, vcc
	v_cndmask_b32_e64 v132, 0, v162, s[0:1]
	v_cndmask_b32_e64 v238, 0, v159, s[0:1]
	s_mov_b64 s[0:1], 0

.LBB0_305:
	ds_read_b128 v[130:133], v188 offset:33280
	ds_read_b128 v[134:137], v188 offset:33296
	ds_read_b128 v[138:141], v188 offset:33536
	ds_read_b128 v[142:145], v188 offset:33552
	ds_read_b128 v[146:149], v188 offset:33792
	ds_read_b128 v[150:153], v188 offset:33808
	ds_read_b128 v[154:157], v188 offset:34048
	ds_read_b128 v[166:169], v188 offset:34064
	s_sub_i32 s0, s21, s0
	v_cmp_gt_i32_e32 vcc, s1, v175
	s_add_i32 s10, s24, 1
	s_min_i32 s10, s10, s20
	v_lshlrev_b32_e32 v170, 16, v124
	v_and_b32_e32 v171, 0xffff0000, v124
	s_lshl_b32 s10, s10, 5
	s_waitcnt lgkmcnt(6)
	v_mul_f32_e32 v238, v130, v130
	v_mul_f32_e32 v239, v131, v131
	v_mul_f32_e32 v240, v132, v132
	v_mul_f32_e32 v241, v133, v133
	v_fmac_f32_e32 v238, v134, v134
	v_fmac_f32_e32 v239, v135, v135
	v_fmac_f32_e32 v240, v136, v136
	v_fmac_f32_e32 v241, v137, v137
	s_waitcnt lgkmcnt(4)
	v_fmac_f32_e32 v238, v138, v138
	v_fmac_f32_e32 v239, v139, v139
	v_fmac_f32_e32 v240, v140, v140
	v_fmac_f32_e32 v241, v141, v141
	v_fmac_f32_e32 v238, v142, v142
	v_fmac_f32_e32 v239, v143, v143
	v_fmac_f32_e32 v240, v144, v144
	v_fmac_f32_e32 v241, v145, v145
	s_waitcnt lgkmcnt(2)
	v_fmac_f32_e32 v238, v146, v146
	v_fmac_f32_e32 v239, v147, v147
	v_fmac_f32_e32 v240, v148, v148
	v_fmac_f32_e32 v241, v149, v149
	v_fmac_f32_e32 v238, v150, v150
	v_fmac_f32_e32 v239, v151, v151
	v_fmac_f32_e32 v240, v152, v152
	v_fmac_f32_e32 v241, v153, v153
	s_waitcnt lgkmcnt(0)
	v_fmac_f32_e32 v238, v154, v154
	v_fmac_f32_e32 v239, v155, v155
	v_fmac_f32_e32 v240, v156, v156
	v_fmac_f32_e32 v241, v157, v157
	v_fmac_f32_e32 v238, v166, v166
	v_fmac_f32_e32 v239, v167, v167
	v_fmac_f32_e32 v240, v168, v168
	v_fmac_f32_e32 v241, v169, v169
	v_add_f32_e32 v238, v238, v239
	v_add_f32_e32 v240, v240, v241
	v_add_f32_e32 v158, v238, v240
	s_nop 1
	v_add_f32_dpp v158, v158, v158 quad_perm:[1,0,3,2] row_mask:0xf bank_mask:0xf
	s_nop 1
	v_add_f32_dpp v158, v158, v158 quad_perm:[2,3,0,1] row_mask:0xf bank_mask:0xf
	s_nop 1
	v_add_f32_dpp v158, v158, v158 row_half_mirror row_mask:0xf bank_mask:0xf
	v_fmamk_f32 v158, v158, 0x3b800000, v206
	v_rsq_f32_e32 v158, v158
	v_mov_b32_e32 v159, s0
	v_cndmask_b32_e32 v159, v210, v159, vcc
	v_add_u32_e32 v162, v159, v175
	v_ashrrev_i32_e32 v163, 31, v162
	v_lshlrev_b64 v[162:163], 13, v[162:163]
	v_lshl_add_u64 v[162:163], v[74:75], 0, v[162:163]
	s_mov_b64 s[0:1], -1
	v_pk_mul_f32 v[130:131], v[130:131], v[158:159] op_sel_hi:[1,0]
	v_lshlrev_b32_e32 v238, 16, v120
	v_and_b32_e32 v239, 0xffff0000, v120
	v_pk_mul_f32 v[130:131], v[130:131], v[238:239]
	v_cvt_pk_bf16_f32 v120, v130, v131
	v_pk_mul_f32 v[132:133], v[132:133], v[158:159] op_sel_hi:[1,0]
	v_lshlrev_b32_e32 v238, 16, v121
	v_and_b32_e32 v239, 0xffff0000, v121
	v_pk_mul_f32 v[132:133], v[132:133], v[238:239]
	v_cvt_pk_bf16_f32 v121, v132, v133
	v_pk_mul_f32 v[134:135], v[134:135], v[158:159] op_sel_hi:[1,0]
	v_lshlrev_b32_e32 v238, 16, v122
	v_and_b32_e32 v239, 0xffff0000, v122
	v_pk_mul_f32 v[134:135], v[134:135], v[238:239]
	v_cvt_pk_bf16_f32 v122, v134, v135
	v_pk_mul_f32 v[136:137], v[136:137], v[158:159] op_sel_hi:[1,0]
	v_lshlrev_b32_e32 v238, 16, v123
	v_and_b32_e32 v239, 0xffff0000, v123
	v_pk_mul_f32 v[136:137], v[136:137], v[238:239]
	v_cvt_pk_bf16_f32 v123, v136, v137
	global_store_dwordx4 v[162:163], v[120:123], off
	v_pk_mul_f32 v[138:139], v[138:139], v[158:159] op_sel_hi:[1,0]
	v_lshlrev_b32_e32 v238, 16, v124
	v_and_b32_e32 v239, 0xffff0000, v124
	v_pk_mul_f32 v[138:139], v[138:139], v[238:239]
	v_cvt_pk_bf16_f32 v124, v138, v139
	v_pk_mul_f32 v[140:141], v[140:141], v[158:159] op_sel_hi:[1,0]
	v_lshlrev_b32_e32 v238, 16, v125
	v_and_b32_e32 v239, 0xffff0000, v125
	v_pk_mul_f32 v[140:141], v[140:141], v[238:239]
	v_cvt_pk_bf16_f32 v125, v140, v141
	v_pk_mul_f32 v[142:143], v[142:143], v[158:159] op_sel_hi:[1,0]
	v_lshlrev_b32_e32 v238, 16, v126
	v_and_b32_e32 v239, 0xffff0000, v126
	v_pk_mul_f32 v[142:143], v[142:143], v[238:239]
	v_cvt_pk_bf16_f32 v126, v142, v143
	v_pk_mul_f32 v[144:145], v[144:145], v[158:159] op_sel_hi:[1,0]
	v_lshlrev_b32_e32 v238, 16, v127
	v_and_b32_e32 v239, 0xffff0000, v127
	v_pk_mul_f32 v[144:145], v[144:145], v[238:239]
	v_cvt_pk_bf16_f32 v127, v144, v145
	global_store_dwordx4 v[162:163], v[124:127], off offset:128
	v_pk_mul_f32 v[146:147], v[146:147], v[158:159] op_sel_hi:[1,0]
	v_lshlrev_b32_e32 v238, 16, v110
	v_and_b32_e32 v239, 0xffff0000, v110
	v_pk_mul_f32 v[146:147], v[146:147], v[238:239]
	v_cvt_pk_bf16_f32 v110, v146, v147
	v_pk_mul_f32 v[148:149], v[148:149], v[158:159] op_sel_hi:[1,0]
	v_lshlrev_b32_e32 v238, 16, v111
	v_and_b32_e32 v239, 0xffff0000, v111
	v_pk_mul_f32 v[148:149], v[148:149], v[238:239]
	v_cvt_pk_bf16_f32 v111, v148, v149
	v_pk_mul_f32 v[150:151], v[150:151], v[158:159] op_sel_hi:[1,0]
	v_lshlrev_b32_e32 v238, 16, v112
	v_and_b32_e32 v239, 0xffff0000, v112
	v_pk_mul_f32 v[150:151], v[150:151], v[238:239]
	v_cvt_pk_bf16_f32 v112, v150, v151
	v_pk_mul_f32 v[152:153], v[152:153], v[158:159] op_sel_hi:[1,0]
	v_lshlrev_b32_e32 v238, 16, v113
	v_and_b32_e32 v239, 0xffff0000, v113
	v_pk_mul_f32 v[152:153], v[152:153], v[238:239]
	v_cvt_pk_bf16_f32 v113, v152, v153
	global_store_dwordx4 v[162:163], v[110:113], off offset:256
	v_pk_mul_f32 v[154:155], v[154:155], v[158:159] op_sel_hi:[1,0]
	v_lshlrev_b32_e32 v238, 16, v88
	v_and_b32_e32 v239, 0xffff0000, v88
	v_pk_mul_f32 v[154:155], v[154:155], v[238:239]
	v_cvt_pk_bf16_f32 v88, v154, v155
	v_pk_mul_f32 v[156:157], v[156:157], v[158:159] op_sel_hi:[1,0]
	v_lshlrev_b32_e32 v238, 16, v89
	v_and_b32_e32 v239, 0xffff0000, v89
	v_pk_mul_f32 v[156:157], v[156:157], v[238:239]
	v_cvt_pk_bf16_f32 v89, v156, v157
	v_pk_mul_f32 v[166:167], v[166:167], v[158:159] op_sel_hi:[1,0]
	v_lshlrev_b32_e32 v238, 16, v116
	v_and_b32_e32 v239, 0xffff0000, v116
	v_pk_mul_f32 v[166:167], v[166:167], v[238:239]
	v_cvt_pk_bf16_f32 v116, v166, v167
	v_pk_mul_f32 v[168:169], v[168:169], v[158:159] op_sel_hi:[1,0]
	v_lshlrev_b32_e32 v238, 16, v117
	v_and_b32_e32 v239, 0xffff0000, v117
	v_pk_mul_f32 v[168:169], v[168:169], v[238:239]
	v_cvt_pk_bf16_f32 v117, v168, v169
	global_store_dwordx2 v[162:163], v[88:89], off offset:384
	global_store_dwordx2 v[162:163], v[116:117], off offset:392
	v_add_u32_e32 v238, s10, v217
	v_ashrrev_i32_e32 v239, 31, v238
	v_lshlrev_b64 v[238:239], 13, v[238:239]
	v_lshl_add_u64 v[238:239], v[78:79], 0, v[238:239]
	global_load_dwordx4 v[120:123], v[238:239], off
	global_load_dwordx4 v[124:127], v[238:239], off offset:128
	global_load_dwordx4 v[110:113], v[238:239], off offset:256
	global_load_dwordx2 v[88:89], v[238:239], off offset:384
	global_load_dwordx2 v[116:117], v[238:239], off offset:392
	s_sub_i32 s10, s17, s10
	s_cmp_gt_i32 s10, 31
	s_cbranch_scc1 .LBB0_307
	s_min_i32 s10, s10, 32
	v_add_f32_e32 v130, 0, v68
	v_cmp_gt_i32_e32 vcc, s10, v176
	v_cmp_gt_i32_e64 s[0:1], s10, v40
	v_and_b32_e32 v133, 0xffff0000, v215
	v_cndmask_b32_e32 v144, 0, v130, vcc
	v_add_f32_e32 v130, 0, v69
	v_cndmask_b32_e32 v143, 0, v130, vcc
	v_lshlrev_b32_e32 v130, 16, v201
	v_cndmask_b32_e32 v141, 0, v130, vcc
	v_and_b32_e32 v130, 0xffff0000, v201
	v_cndmask_b32_e32 v169, 0, v130, vcc
	v_cmp_gt_i32_e32 vcc, s10, v1
	v_lshlrev_b32_e32 v132, 16, v202
	v_cndmask_b32_e64 v138, 0, v132, s[0:1]
	v_cndmask_b32_e32 v130, 0, v104, vcc
	v_add_f32_e32 v142, v144, v130
	v_lshlrev_b32_e32 v130, 16, v215
	v_cndmask_b32_e32 v140, 0, v130, vcc
	v_cndmask_b32_e32 v131, 0, v105, vcc
	v_cndmask_b32_e64 v130, 0, v76, s[0:1]
	v_pk_add_f32 v[146:147], v[130:131], v[142:143]
	v_cndmask_b32_e64 v130, 0, v77, s[0:1]
	v_add_f32_e32 v241, v130, v147
	v_cndmask_b32_e32 v139, 0, v133, vcc
	v_and_b32_e32 v130, 0xffff0000, v202
	v_cmp_gt_i32_e32 vcc, s10, v3
	v_cndmask_b32_e64 v166, 0, v130, s[0:1]
	v_and_b32_e32 v131, 0xffff0000, v197
	v_cndmask_b32_e32 v130, 0, v72, vcc
	v_add_f32_e32 v239, v130, v146
	v_cndmask_b32_e32 v130, 0, v73, vcc
	v_add_f32_e32 v240, v130, v241
	v_lshlrev_b32_e32 v130, 16, v200
	v_cndmask_b32_e32 v135, 0, v130, vcc
	v_and_b32_e32 v130, 0xffff0000, v200
	v_cndmask_b32_e32 v159, 0, v130, vcc
	v_cmp_gt_i32_e32 vcc, s10, v43
	v_cmp_gt_i32_e64 s[0:1], s10, v42
	v_and_b32_e32 v133, 0xffff0000, v196
	v_cndmask_b32_e32 v130, 0, v70, vcc
	v_add_f32_e32 v173, v130, v239
	v_cndmask_b32_e32 v130, 0, v71, vcc
	v_add_f32_e32 v238, v130, v240
	v_lshlrev_b32_e32 v130, 16, v197
	v_cndmask_b32_e32 v134, 0, v130, vcc
	v_lshlrev_b32_e32 v130, 16, v198
	v_cndmask_b32_e64 v132, 0, v62, s[0:1]
	v_cndmask_b32_e32 v137, 0, v131, vcc
	v_cndmask_b32_e64 v136, 0, v130, s[0:1]
	v_and_b32_e32 v130, 0xffff0000, v198
	v_cmp_gt_i32_e32 vcc, s10, v45
	v_add_f32_e32 v171, v132, v173
	v_cndmask_b32_e64 v132, 0, v63, s[0:1]
	v_cndmask_b32_e64 v131, 0, v130, s[0:1]
	v_cndmask_b32_e32 v130, 0, v66, vcc
	v_add_f32_e32 v172, v132, v238
	v_add_f32_e32 v168, v130, v171
	v_cndmask_b32_e32 v130, 0, v67, vcc
	v_cmp_gt_i32_e64 s[0:1], s10, v44
	v_add_f32_e32 v170, v130, v172
	v_lshlrev_b32_e32 v130, 16, v196
	v_cndmask_b32_e64 v148, 0, v65, s[0:1]
	v_lshlrev_b32_e32 v132, 16, v225
	v_cndmask_b32_e64 v145, 0, v64, s[0:1]
	v_add_f32_e32 v167, v148, v170
	v_and_b32_e32 v148, 0xffff0000, v225
	v_cndmask_b32_e32 v130, 0, v130, vcc
	v_add_f32_e32 v145, v145, v168
	v_cndmask_b32_e32 v133, 0, v133, vcc
	v_cndmask_b32_e64 v132, 0, v132, s[0:1]
	v_cndmask_b32_e64 v158, 0, v148, s[0:1]
	s_mov_b64 s[0:1], 0
